# arrival-check poll: 16 serialized counter loads issued in parallel with one wait (on top of bar_top)
# baseline (speedup 1.0000x reference)
.LBB0_792:
	v_readlane_b32 s14, v252, 56
	v_readlane_b32 s15, v252, 57
	s_mov_b64 s[16:17], -1
	s_nop 4
	global_load_dword v0, v99, s[14:15] sc1
	v_readlane_b32 s14, v252, 58
	v_readlane_b32 s15, v252, 59
	s_nop 4
	global_load_dword v1, v99, s[14:15] sc1
	v_readlane_b32 s14, v252, 60
	v_readlane_b32 s15, v252, 61
	s_nop 4
	global_load_dword v2, v99, s[14:15] sc1
	v_readlane_b32 s14, v252, 62
	v_readlane_b32 s15, v252, 63
	s_nop 4
	global_load_dword v3, v99, s[14:15] sc1
	v_readlane_b32 s14, v253, 0
	v_readlane_b32 s15, v253, 1
	s_nop 4
	global_load_dword v4, v99, s[14:15] sc1
	v_readlane_b32 s14, v253, 2
	v_readlane_b32 s15, v253, 3
	s_nop 4
	global_load_dword v5, v99, s[14:15] sc1
	v_readlane_b32 s14, v253, 4
	v_readlane_b32 s15, v253, 5
	s_nop 4
	global_load_dword v6, v99, s[14:15] sc1
	v_readlane_b32 s14, v253, 6
	v_readlane_b32 s15, v253, 7
	s_nop 4
	global_load_dword v7, v99, s[14:15] sc1
	v_readlane_b32 s14, v253, 8
	v_readlane_b32 s15, v253, 9
	s_nop 4
	global_load_dword v8, v99, s[14:15] sc1
	v_readlane_b32 s14, v253, 10
	v_readlane_b32 s15, v253, 11
	s_nop 4
	global_load_dword v9, v99, s[14:15] sc1
	v_readlane_b32 s14, v253, 12
	v_readlane_b32 s15, v253, 13
	s_nop 4
	global_load_dword v10, v99, s[14:15] sc1
	v_readlane_b32 s14, v253, 14
	v_readlane_b32 s15, v253, 15
	s_nop 4
	global_load_dword v11, v99, s[14:15] sc1
	v_readlane_b32 s14, v253, 16
	v_readlane_b32 s15, v253, 17
	s_nop 4
	global_load_dword v12, v99, s[14:15] sc1
	v_readlane_b32 s14, v253, 18
	v_readlane_b32 s15, v253, 19
	s_nop 4
	global_load_dword v13, v99, s[14:15] sc1
	v_readlane_b32 s14, v253, 20
	v_readlane_b32 s15, v253, 21
	s_nop 4
	global_load_dword v14, v99, s[14:15] sc1
	v_readlane_b32 s14, v253, 22
	v_readlane_b32 s15, v253, 23
	s_nop 4
	global_load_dword v15, v99, s[14:15] sc1
	s_mov_b64 s[14:15], -1
	s_waitcnt vmcnt(0)
	v_add_u32_e32 v16, v1, v0
	v_add_u32_e32 v16, v16, v2
	v_add_u32_e32 v16, v16, v3
	v_add_u32_e32 v16, v16, v4
	v_add_u32_e32 v16, v16, v5
	v_add_u32_e32 v16, v16, v6
	v_add_u32_e32 v16, v16, v7
	v_add_u32_e32 v16, v16, v8
	v_add_u32_e32 v16, v16, v9
	v_add_u32_e32 v16, v16, v10
	v_add_u32_e32 v16, v16, v11
	v_add_u32_e32 v16, v16, v12
	v_add_u32_e32 v16, v16, v13
	v_add_u32_e32 v16, v16, v14
	v_add_u32_e32 v16, v16, v15
	v_cmp_eq_u32_e32 vcc, s24, v16
	s_cbranch_vccnz .LBB0_791
	s_and_b32 s14, s25, 0xff
	s_cmp_eq_u32 s14, 0
	s_mov_b64 s[14:15], -1
	s_mov_b64 s[18:19], -1
	s_sleep 1
	s_cbranch_scc1 .LBB0_796
	s_and_b64 vcc, exec, s[18:19]
	s_cbranch_vccz .LBB0_791
